# mixers sample rows: every workgroup runs four attention tasks and, concurrently on its other four waves, sixteen S5 tasks (no workgroup barrier between the parts)
# speedup vs baseline: 1.0063x; 1.0063x over previous
; DI void mixers_phase(ArgsP a, LAS unsigned char* lds, int l, int tid) {
;     ...
;     const int wave = tid >> 6, lane = tid & 63, gw = blockIdx.x * 8 + wave, NGW = gridDim.x * 8;
;     const int vcb = (gridDim.x % 8 == 0) ? (blockIdx.x % 8) * (gridDim.x / 8) + blockIdx.x / 8 : blockIdx.x;
;     for (int rp = 0; rp < 1 + ((MIXM >> 0) & 1); ++rp) for (int u = vcb; u < 256; u += gridDim.x) attn_prompt_unit(lds, u, Q, KB, VB, YB, a->in[16] + l * 8, tid);
;     for (int rp = 0; rp < 1 + ((MIXM >> 1) & 1); ++rp) for (int t = vcb; t < 256; t += gridDim.x) s5_prompt_task(lds, t, l, a, U, YC0, tid);
;     for (int rp = 0; rp < 1 + ((MIXM >> 2) & 1); ++rp) for (int t = gw; t < 4096; t += NGW) s5_sample_task(lds, t, l, a, U, YC0, tid);
;     __syncthreads();
;     for (int rp = 0; rp < 1 + ((MIXM >> 3) & 1); ++rp) for (int t = gw; t < 1024; t += NGW) attn_sample_task(lds + wave * 4096, t, l, a, Q, YB, lane);
.LBB0_954:
	v_add_u32_e32 v100, s83, v157
	v_mov_b32_e32 v101, v100
	v_mov_b32_e32 v234, s48
	s_cmpk_lg_i32 s82, 0x100
	s_cbranch_scc1 .Ls5s_orig
	s_lshr_b32 s8, s83, 3
	s_and_b32 s9, s8, 1
	v_lshrrev_b32_e32 v234, 2, v157
	v_cmp_eq_u32_e32 vcc, s9, v234
	s_lshr_b32 s10, s8, 1
	s_lshl_b32 s10, s10, 3
	v_add_u32_e32 v100, s10, v157
	v_mov_b32_e32 v235, 0x7fff0000
	v_cndmask_b32_e32 v100, v235, v100, vcc
	s_lshl_b32 s10, s8, 2
	v_and_b32_e32 v101, 3, v157
	v_add_u32_e32 v101, s10, v101
	v_mov_b32_e32 v235, -1
	v_cndmask_b32_e32 v101, v101, v235, vcc
	v_mov_b32_e32 v234, 0x400

; #define LAS __attribute__((address_space(3)))
; DI float bf2f(bf16_t b) { return __uint_as_float((unsigned)b << 16); }
; DI void attn_sample_task(LAS unsigned char* wl, int task, int l, ArgsP a, const bf16_t* Q, bf16_t* YB, int lane) {
;     const int b = task >> 3, h = task & 7, g = h >> 2;
;     LAS float* qs = (LAS float*)wl;
;     LAS float* ps = qs + 256;
; #pragma unroll
;     for (int t = 0; t < 4; ++t) qs[t * 64 + lane] = bf2f(Q[(size_t)(MP + b * 4 + t) * 512 + h * 64 + lane]);
;     const float* ck = a->in[2] + (size_t)(l * 128 + b) * 128 * 128 + g * 64;
;     const float* cv = a->in[3] + (size_t)(l * 128 + b) * 128 * 128 + g * 64;
;     const float* nk = a->out + OFF_KS + ((size_t)(l * 128 + b) * 128 + 124) * 128 + g * 64;
;     const float* nv = a->out + OFF_VS + ((size_t)(l * 128 + b) * 128 + 124) * 128 + g * 64;
;     const float sink = a->in[16][l * 8 + h];
;     float mx[4] = {sink, sink, sink, sink};
; DI void mixers_phase(ArgsP a, LAS unsigned char* lds, int l, int tid) {
;     ...
;     __syncthreads();
;     for (int rp = 0; rp < 1 + ((MIXM >> 3) & 1); ++rp) for (int t = gw; t < 1024; t += NGW) attn_sample_task(lds + wave * 4096, t, l, a, Q, YB, lane);
.LBB0_965:
	s_or_b64 exec, exec, s[30:31]
	s_movk_i32 s4, 0x400
	v_cmp_gt_i32_e32 vcc, s4, v100
	s_waitcnt vmcnt(0) lgkmcnt(0)
	s_cmpk_eq_i32 s82, 0x100
	s_cbranch_scc1 .Lat_nobar
	s_barrier
.Lat_nobar:
	s_and_saveexec_b64 s[4:5], vcc
	s_mov_b32 s42, 0x800000
	s_cbranch_execz .LBB0_1004
	s_load_dwordx2 s[6:7], s[34:35], 0x80
	s_load_dwordx4 s[28:31], s[34:35], 0x10
	v_bfe_u32 v4, v194, 6, 3
	v_readlane_b32 s8, v254, 37
	v_mov_b32_e32 v131, v97
	s_movk_i32 s16, 0x88
	v_or_b32_e32 v0, s8, v4
	v_ashrrev_i32_e32 v1, 31, v0
	s_waitcnt lgkmcnt(0)
	v_lshl_add_u64 v[0:1], v[0:1], 2, s[6:7]
	global_load_dword v41, v[0:1], off
	v_or_b32_e32 v0, 0x80, v133
	s_movk_i32 s18, 0x82
	s_movk_i32 s20, 0x83
	v_lshl_add_u64 v[2:3], s[0:1], 0, v[130:131]
	v_lshlrev_b32_e32 v4, 7, v4
	v_mov_b32_e32 v5, v97
	v_cmp_gt_u32_e64 s[14:15], s66, v0
	v_cmp_gt_u32_e64 s[16:17], s16, v0
	v_cmp_gt_u32_e64 s[18:19], s18, v0
	v_cmp_gt_u32_e64 s[20:21], s20, v0
	v_lshl_add_u64 v[0:1], s[2:3], 0, v[130:131]
	v_lshl_add_u64 v[8:9], v[2:3], 0, v[4:5]
	v_and_b32_e32 v2, 0x100, v194
	v_mov_b32_e32 v3, v97
	v_lshl_add_u64 v[6:7], s[24:25], 0, v[2:3]
	s_mov_b64 s[0:1], 0x6770000
	v_lshl_add_u64 v[12:13], v[0:1], 0, v[4:5]
	v_lshl_or_b32 v0, v133, 9, v2
	v_mov_b32_e32 v1, v97
	v_lshl_add_u64 v[10:11], v[6:7], 0, s[0:1]
	v_lshl_add_u64 v[4:5], s[28:29], 0, v[0:1]
	s_mov_b64 s[0:1], 0x8020
	v_lshl_add_u64 v[16:17], v[4:5], 0, s[0:1]
	v_lshl_add_u64 v[0:1], s[24:25], 0, v[0:1]
	s_mov_b64 s[0:1], 0x477f820
	v_lshlrev_b32_e32 v20, 12, v157
	s_cmpk_lg_i32 s82, 0x100
	s_cbranch_scc1 .Lat_lds
	s_bitcmp1_b32 s83, 3
	s_cbranch_scc0 .Lat_lds
	v_add_u32_e32 v20, 0xc000, v20
.Lat_lds:
	v_lshl_add_u64 v[18:19], v[0:1], 0, s[0:1]
	s_add_i32 s0, 0, 0x400
	v_readlane_b32 s9, v254, 38
	v_add_u32_e32 v43, 0, v20
	v_lshlrev_b32_e32 v96, 2, v133
	v_add_u32_e32 v68, s0, v20
	v_lshl_add_u64 v[0:1], s[30:31], 0, v[2:3]
	s_mov_b64 s[0:1], 0xa00
	v_add_u32_e32 v47, v43, v96
	v_cmp_eq_u32_e64 s[6:7], 0, v133
	v_cmp_lt_u32_e64 s[8:9], 1, v133
	v_cmp_lt_u32_e64 s[10:11], 2, v133
	v_cmp_lt_u32_e64 s[12:13], 3, v133
	v_xor_b32_e32 v53, 4, v96
	v_xor_b32_e32 v59, 8, v96
	v_xor_b32_e32 v64, 16, v96
	v_xor_b32_e32 v65, 32, v96
	v_xor_b32_e32 v66, 64, v96
	v_xor_b32_e32 v67, 0x80, v96
	v_lshl_add_u64 v[14:15], v[4:5], 0, 32
	v_mov_b32_e32 v20, v96
	v_mov_b32_e32 v21, v97
	v_lshl_add_u64 v[22:23], v[0:1], 0, s[0:1]
	s_mov_b64 s[0:1], 0
	s_branch .LBB0_968
